# GLA state item: LDS spin barriers replaced by s_barrier (both halves of the workgroup run these items together)
# speedup vs baseline: 1.0512x; 1.0054x over previous
; DI float logsigf_(float x) { return fminf(x, 0.f) - __logf(1.f + __expf(-fabsf(x))); }
; DN void gla_state_item(const Params& p, int l, int item, char* smem) {
;     ...
;   for (int c = 0; c < 36; ++c) {
;     int cs = (dir == 0) ? (c < 4 ? 32 + c : c - 4) : (c < 4 ? 35 - c : 35 - c);
;     size_t m0 = (size_t)b * TT + cs * 64;
;     vsync();
;     {
;       float t8[8];
;       { const int li = tid >> 2, d8 = (tid & 3) * 8; unpack8(*(const u32x4*)(P + (m0 + li) * PW + 2048 + hh * 32 + d8), t8);
; #pragma unroll
;         for (int e = 0; e < 8; ++e) kk_[li * 33 + d8 + e] = t8[e]; }
; #pragma unroll
;       for (int i = 0; i < 2; ++i) { const int c = tid + 256 * i, li = c >> 3, e8 = (c & 7) * 8; unpack8(*(const u32x4*)(P + (m0 + li) * PW + 2176 + hh * 64 + e8), t8);
;         *(f32x4v*)(vv + li * 64 + e8) = (f32x4v){t8[0], t8[1], t8[2], t8[3]}; *(f32x4v*)(vv + li * 64 + e8 + 4) = (f32x4v){t8[4], t8[5], t8[6], t8[7]}; }
;       if (tid < 128) { const int li = tid >> 1, q8 = (tid & 1) * 8; unpack8(*(const u32x4*)(P + (m0 + li) * PW + 2432 + dir * 16 + q8), t8);
;         *(f32x4v*)(gg + li * 16 + q8) = (f32x4v){t8[0], t8[1], t8[2], t8[3]}; *(f32x4v*)(gg + li * 16 + q8 + 4) = (f32x4v){t8[4], t8[5], t8[6], t8[7]}; }
;     }
;     vsync();
;     {
;       float lgv[8];
; #pragma unroll
;       for (int li = 0; li < 8; ++li) {
;         int lt = lgrp * 8 + li;
;         float x = abv;
; #pragma unroll
;         for (int q = 0; q < 16; ++q) x += gg[lt * 16 + q] * a2c[q];
;         lgv[li] = logsigf_(x) * (1.f / 16.f);
.LBB0_426:
	s_waitcnt lgkmcnt(0)
	s_barrier
	s_cmp_lt_u32 s66, 4
	s_cselect_b32 s42, 32, -4
	s_add_i32 s56, s42, s66
	s_sub_i32 s57, 35, s66
	s_and_b64 s[42:43], s[52:53], exec
	s_cselect_b32 s56, s56, s57
	s_lshl_b32 s42, s56, 6
	s_ashr_i32 s43, s42, 31
	v_lshl_add_u64 v[44:45], v[20:21], 0, s[42:43]
	v_lshl_add_u64 v[46:47], v[44:45], 0, v[22:23]
	v_mov_b64_e32 v[50:51], s[84:85]
	v_mad_u64_u32 v[48:49], s[42:43], v46, s88, v[50:51]
	v_mov_b32_e32 v46, v49
	v_mad_u64_u32 v[46:47], s[42:43], v47, s88, v[46:47]
	v_mov_b32_e32 v49, v46
	v_lshl_add_u64 v[46:47], v[48:49], 0, v[152:153]
	v_mov_b32_e32 v37, v153
	v_lshl_add_u64 v[46:47], v[46:47], 0, v[36:37]
	v_add_co_u32_e32 v46, vcc, s96, v46
	s_nop 1
	v_addc_co_u32_e32 v47, vcc, 0, v47, vcc
	global_load_dwordx4 v[46:49], v[46:47], off
	s_waitcnt vmcnt(0)
	v_lshlrev_b32_e32 v37, 16, v46
	v_and_b32_e32 v39, 0xffff0000, v46
	v_lshlrev_b32_e32 v41, 16, v47
	v_and_b32_e32 v43, 0xffff0000, v47
	v_lshlrev_b32_e32 v46, 16, v48
	v_and_b32_e32 v47, 0xffff0000, v48
	v_lshlrev_b32_e32 v48, 16, v49
	v_and_b32_e32 v49, 0xffff0000, v49
	ds_write2_b32 v62, v37, v39 offset1:1
	ds_write2_b32 v62, v41, v43 offset0:2 offset1:3
	ds_write2_b32 v62, v46, v47 offset0:4 offset1:5
	ds_write2_b32 v62, v48, v49 offset0:6 offset1:7
	v_lshl_add_u64 v[46:47], v[44:45], 0, v[18:19]
	v_mad_u64_u32 v[48:49], s[42:43], v46, s88, v[50:51]
	v_mov_b32_e32 v46, v49
	v_mad_u64_u32 v[46:47], s[42:43], v47, s88, v[46:47]
	v_mov_b32_e32 v49, v46
	v_mov_b32_e32 v39, v153
	v_lshl_add_u64 v[46:47], v[48:49], 0, v[38:39]
	v_mov_b32_e32 v41, v153
	v_lshl_add_u64 v[46:47], v[46:47], 0, v[40:41]
	v_add_co_u32_e32 v46, vcc, s96, v46
	s_nop 1
	v_addc_co_u32_e32 v47, vcc, 0, v47, vcc
	global_load_dwordx4 v[46:49], v[46:47], off offset:256
	s_waitcnt vmcnt(0)
	v_lshlrev_b32_e32 v66, 16, v46
	v_and_b32_e32 v67, 0xffff0000, v46
	v_lshlrev_b32_e32 v68, 16, v47
	v_and_b32_e32 v69, 0xffff0000, v47
	v_lshlrev_b32_e32 v46, 16, v48
	v_and_b32_e32 v47, 0xffff0000, v48
	v_lshlrev_b32_e32 v48, 16, v49
	v_and_b32_e32 v49, 0xffff0000, v49
	ds_write_b128 v63, v[66:69] offset:8448
	ds_write_b128 v63, v[46:49] offset:8464
	v_lshl_add_u64 v[46:47], v[44:45], 0, v[30:31]
	v_mad_u64_u32 v[48:49], s[42:43], v46, s88, v[50:51]
	v_mov_b32_e32 v46, v49
	v_mad_u64_u32 v[46:47], s[42:43], v47, s88, v[46:47]
	v_mov_b32_e32 v49, v46
	v_lshl_add_u64 v[46:47], v[48:49], 0, v[38:39]
	v_lshl_add_u64 v[46:47], v[46:47], 0, v[40:41]
	v_add_co_u32_e32 v46, vcc, s96, v46
	s_nop 1
	v_addc_co_u32_e32 v47, vcc, 0, v47, vcc
	global_load_dwordx4 v[46:49], v[46:47], off offset:256
	s_waitcnt vmcnt(0)
	v_lshlrev_b32_e32 v66, 16, v46
	v_and_b32_e32 v67, 0xffff0000, v46
	v_lshlrev_b32_e32 v68, 16, v47
	v_and_b32_e32 v69, 0xffff0000, v47
	v_lshlrev_b32_e32 v46, 16, v48
	v_and_b32_e32 v47, 0xffff0000, v48
	v_lshlrev_b32_e32 v48, 16, v49
	v_and_b32_e32 v49, 0xffff0000, v49
	ds_write_b128 v65, v[66:69] offset:8448
	ds_write_b128 v65, v[46:49] offset:8464
	s_and_saveexec_b64 s[42:43], s[2:3]
	s_cbranch_execz .LBB0_432
	v_lshl_add_u64 v[44:45], v[44:45], 0, v[24:25]
	v_mov_b64_e32 v[46:47], s[84:85]
	v_mad_u64_u32 v[46:47], s[58:59], v44, s88, v[46:47]
	v_mov_b32_e32 v44, v47
	v_mad_u64_u32 v[44:45], s[58:59], v45, s88, v[44:45]
	v_mov_b32_e32 v47, v44
	v_lshl_add_u64 v[44:45], v[46:47], 0, s[80:81]
	v_mov_b32_e32 v43, v153
	v_lshl_add_u64 v[44:45], v[44:45], 0, v[42:43]
	v_add_co_u32_e32 v44, vcc, 0x1000, v44
	s_nop 1
	v_addc_co_u32_e32 v45, vcc, 0, v45, vcc
	global_load_dwordx4 v[44:47], v[44:45], off offset:768
	s_waitcnt vmcnt(0)
	v_lshlrev_b32_e32 v48, 16, v44
	v_and_b32_e32 v49, 0xffff0000, v44
	v_lshlrev_b32_e32 v50, 16, v45
	v_and_b32_e32 v51, 0xffff0000, v45
	v_lshlrev_b32_e32 v44, 16, v46
	v_and_b32_e32 v45, 0xffff0000, v46
	v_lshlrev_b32_e32 v46, 16, v47
	v_and_b32_e32 v47, 0xffff0000, v47
	ds_write_b128 v59, v[48:51] offset:33280
	ds_write_b128 v59, v[44:47] offset:33296
.LBB0_432:
	s_or_b64 exec, exec, s[42:43]
	s_waitcnt lgkmcnt(0)
	s_waitcnt lgkmcnt(0)
	s_barrier
	ds_read_b128 v[44:47], v64 offset:33280
	ds_read_b128 v[48:51], v64 offset:33296
	ds_read_b128 v[66:69], v64 offset:33312
	ds_read_b128 v[70:73], v64 offset:33328
	s_mov_b32 s57, 0xbfb8aa3b
	s_waitcnt lgkmcnt(3)
	v_fma_f32 v37, v52, v44, v58
	v_fmac_f32_e32 v37, v53, v45
	v_fmac_f32_e32 v37, v54, v46
	v_fmac_f32_e32 v37, v55, v47
	s_waitcnt lgkmcnt(2)
	v_fmac_f32_e32 v37, v56, v48
	v_fmac_f32_e32 v37, v57, v49
	v_pk_mul_f32 v[44:45], v[8:9], v[50:51]
	s_mov_b32 s59, 0x3f317217
	v_add_f32_e32 v37, v37, v44
	v_add_f32_e32 v37, v37, v45
	s_waitcnt lgkmcnt(1)
	v_pk_mul_f32 v[44:45], v[10:11], v[66:67]
	ds_read_b128 v[46:49], v64 offset:33344
	v_add_f32_e32 v37, v37, v44
	v_add_f32_e32 v37, v37, v45
	v_pk_mul_f32 v[44:45], v[12:13], v[68:69]
	s_mov_b32 s58, 0x7f800000
	v_add_f32_e32 v37, v37, v44
	v_add_f32_e32 v37, v37, v45
	s_waitcnt lgkmcnt(1)
	v_pk_mul_f32 v[44:45], v[14:15], v[70:71]
	s_mov_b32 s60, 0x3d800000
	v_add_f32_e32 v37, v37, v44
	v_add_f32_e32 v37, v37, v45
	v_pk_mul_f32 v[44:45], v[16:17], v[72:73]
	s_nop 0
	v_add_f32_e32 v37, v37, v44
	v_add_f32_e32 v37, v37, v45
	v_min_f32_e32 v44, 0, v37
	v_mul_f32_e64 v37, |v37|, s57
	v_exp_f32_e32 v37, v37
	s_nop 0
	v_add_f32_e32 v37, 1.0, v37
	v_cmp_gt_f32_e32 vcc, s33, v37
	s_nop 1
	v_cndmask_b32_e64 v39, 0, 32, vcc
	v_ldexp_f32 v37, v37, v39
	v_log_f32_e32 v37, v37
	s_nop 0
	v_mul_f32_e32 v39, 0x3f317217, v37
	v_fma_f32 v39, v37, s59, -v39
	v_fmac_f32_e32 v39, 0x3377d1cf, v37
	v_fmac_f32_e32 v39, 0x3f317217, v37
	v_cmp_lt_f32_e64 s[42:43], |v37|, s58
	s_nop 1
	v_cndmask_b32_e64 v37, v37, v39, s[42:43]
	v_cndmask_b32_e32 v39, 0, v196, vcc
	v_sub_f32_e32 v50, v37, v39
	s_waitcnt lgkmcnt(0)
; DI float logsigf_(float x) { return fminf(x, 0.f) - __logf(1.f + __expf(-fabsf(x))); }
; DN void gla_state_item(const Params& p, int l, int item, char* smem) {
;     ...
; #pragma unroll
;       for (int li = 0; li < 8; ++li) {
;         int lt = lgrp * 8 + li;
;         float x = abv;
; #pragma unroll
;         for (int q = 0; q < 16; ++q) x += gg[lt * 16 + q] * a2c[q];
;         lgv[li] = logsigf_(x) * (1.f / 16.f);
	v_fma_f32 v37, v52, v46, v58
	v_fmac_f32_e32 v37, v53, v47
	v_fmac_f32_e32 v37, v54, v48
	v_fmac_f32_e32 v37, v55, v49
	ds_read_b128 v[46:49], v64 offset:33360
	s_waitcnt lgkmcnt(0)
	v_fmac_f32_e32 v37, v56, v46
	v_fmac_f32_e32 v37, v57, v47
	v_pk_mul_f32 v[46:47], v[8:9], v[48:49]
	s_nop 0
	v_add_f32_e32 v37, v37, v46
	v_add_f32_e32 v37, v37, v47
	ds_read_b128 v[46:49], v64 offset:33376
	s_waitcnt lgkmcnt(0)
	v_pk_mul_f32 v[46:47], v[10:11], v[46:47]
	s_nop 0
	v_add_f32_e32 v37, v37, v46
	v_add_f32_e32 v37, v37, v47
	v_pk_mul_f32 v[46:47], v[12:13], v[48:49]
	s_nop 0
	v_add_f32_e32 v37, v37, v46
	v_add_f32_e32 v37, v37, v47
	ds_read_b128 v[46:49], v64 offset:33392
	s_waitcnt lgkmcnt(0)
	v_pk_mul_f32 v[46:47], v[14:15], v[46:47]
	s_nop 0
	v_add_f32_e32 v37, v37, v46
	v_add_f32_e32 v37, v37, v47
	v_pk_mul_f32 v[46:47], v[16:17], v[48:49]
	s_nop 0
	v_add_f32_e32 v37, v37, v46
	v_add_f32_e32 v37, v37, v47
	v_min_f32_e32 v45, 0, v37
	v_mul_f32_e64 v37, |v37|, s57
	v_exp_f32_e32 v37, v37
	ds_read_b128 v[46:49], v64 offset:33408
	v_add_f32_e32 v37, 1.0, v37
	v_cmp_gt_f32_e32 vcc, s33, v37
	s_nop 1
	v_cndmask_b32_e64 v39, 0, 32, vcc
	v_ldexp_f32 v37, v37, v39
	v_log_f32_e32 v37, v37
	s_nop 0
	v_mul_f32_e32 v39, 0x3f317217, v37
	v_fma_f32 v39, v37, s59, -v39
	v_fmac_f32_e32 v39, 0x3377d1cf, v37
	v_fmac_f32_e32 v39, 0x3f317217, v37
	v_cmp_lt_f32_e64 s[42:43], |v37|, s58
	s_nop 1
	v_cndmask_b32_e64 v37, v37, v39, s[42:43]
	v_cndmask_b32_e32 v39, 0, v196, vcc
	v_sub_f32_e32 v51, v37, v39
	s_waitcnt lgkmcnt(0)
	v_fma_f32 v37, v52, v46, v58
	v_fmac_f32_e32 v37, v53, v47
	v_fmac_f32_e32 v37, v54, v48
	v_fmac_f32_e32 v37, v55, v49
	ds_read_b128 v[46:49], v64 offset:33424
	v_pk_add_f32 v[44:45], v[44:45], v[50:51] neg_lo:[0,1] neg_hi:[0,1]
	s_waitcnt lgkmcnt(0)
	v_fmac_f32_e32 v37, v56, v46
	v_fmac_f32_e32 v37, v57, v47
	v_pk_mul_f32 v[46:47], v[8:9], v[48:49]
	v_pk_mul_f32 v[44:45], v[44:45], s[60:61] op_sel_hi:[1,0]
	v_add_f32_e32 v37, v37, v46
	v_add_f32_e32 v37, v37, v47
	ds_read_b128 v[46:49], v64 offset:33440
	s_waitcnt lgkmcnt(0)
	v_pk_mul_f32 v[46:47], v[10:11], v[46:47]
	s_nop 0
	v_add_f32_e32 v37, v37, v46
	v_add_f32_e32 v37, v37, v47
	v_pk_mul_f32 v[46:47], v[12:13], v[48:49]
	s_nop 0
	v_add_f32_e32 v37, v37, v46
	v_add_f32_e32 v37, v37, v47
	ds_read_b128 v[46:49], v64 offset:33456
	s_waitcnt lgkmcnt(0)
	v_pk_mul_f32 v[46:47], v[14:15], v[46:47]
	s_nop 0
	v_add_f32_e32 v37, v37, v46
	v_add_f32_e32 v37, v37, v47
	v_pk_mul_f32 v[46:47], v[16:17], v[48:49]
	ds_read_b128 v[48:51], v64 offset:33472
	v_add_f32_e32 v37, v37, v46
	v_add_f32_e32 v37, v37, v47
	v_min_f32_e32 v46, 0, v37
	v_mul_f32_e64 v37, |v37|, s57
	v_exp_f32_e32 v37, v37
	s_nop 0
	v_add_f32_e32 v37, 1.0, v37
	v_cmp_gt_f32_e32 vcc, s33, v37
	s_nop 1
	v_cndmask_b32_e64 v39, 0, 32, vcc
	v_ldexp_f32 v37, v37, v39
	v_log_f32_e32 v37, v37
	s_nop 0
	v_mul_f32_e32 v39, 0x3f317217, v37
	v_fma_f32 v39, v37, s59, -v39
	v_fmac_f32_e32 v39, 0x3377d1cf, v37
	v_fmac_f32_e32 v39, 0x3f317217, v37
	v_cmp_lt_f32_e64 s[42:43], |v37|, s58
	s_nop 1
	v_cndmask_b32_e64 v37, v37, v39, s[42:43]
	v_cndmask_b32_e32 v39, 0, v196, vcc
	v_sub_f32_e32 v66, v37, v39
	s_waitcnt lgkmcnt(0)
	v_fma_f32 v37, v52, v48, v58
	v_fmac_f32_e32 v37, v53, v49
	v_fmac_f32_e32 v37, v54, v50
	v_fmac_f32_e32 v37, v55, v51
	ds_read_b128 v[48:51], v64 offset:33488
	s_waitcnt lgkmcnt(0)
	v_fmac_f32_e32 v37, v56, v48
	v_fmac_f32_e32 v37, v57, v49
	v_pk_mul_f32 v[48:49], v[8:9], v[50:51]
	s_nop 0
	v_add_f32_e32 v37, v37, v48
	v_add_f32_e32 v37, v37, v49
	ds_read_b128 v[48:51], v64 offset:33504
	s_waitcnt lgkmcnt(0)
	v_pk_mul_f32 v[48:49], v[10:11], v[48:49]
	s_nop 0
	v_add_f32_e32 v37, v37, v48
	v_add_f32_e32 v37, v37, v49
	v_pk_mul_f32 v[48:49], v[12:13], v[50:51]
	s_nop 0
	v_add_f32_e32 v37, v37, v48
	v_add_f32_e32 v37, v37, v49
	ds_read_b128 v[48:51], v64 offset:33520
	s_waitcnt lgkmcnt(0)
	v_pk_mul_f32 v[48:49], v[14:15], v[48:49]
	s_nop 0
	v_add_f32_e32 v37, v37, v48
	v_add_f32_e32 v37, v37, v49
	v_pk_mul_f32 v[48:49], v[16:17], v[50:51]
	s_nop 0
	v_add_f32_e32 v37, v37, v48
	v_add_f32_e32 v37, v37, v49
	v_min_f32_e32 v47, 0, v37
	v_mul_f32_e64 v37, |v37|, s57
	v_exp_f32_e32 v37, v37
	ds_read_b128 v[48:51], v64 offset:33536
	v_add_f32_e32 v37, 1.0, v37
	v_cmp_gt_f32_e32 vcc, s33, v37
	s_nop 1
	v_cndmask_b32_e64 v39, 0, 32, vcc
	v_ldexp_f32 v37, v37, v39
	v_log_f32_e32 v37, v37
	s_nop 0
	v_mul_f32_e32 v39, 0x3f317217, v37
	v_fma_f32 v39, v37, s59, -v39
	v_fmac_f32_e32 v39, 0x3377d1cf, v37
	v_fmac_f32_e32 v39, 0x3f317217, v37
	v_cmp_lt_f32_e64 s[42:43], |v37|, s58
	s_nop 1
	v_cndmask_b32_e64 v37, v37, v39, s[42:43]
	v_cndmask_b32_e32 v39, 0, v196, vcc
	v_sub_f32_e32 v67, v37, v39
	v_pk_add_f32 v[46:47], v[46:47], v[66:67] neg_lo:[0,1] neg_hi:[0,1]
	ds_read_b128 v[66:69], v64 offset:33600
	s_waitcnt lgkmcnt(1)
	v_fma_f32 v37, v52, v48, v58
	v_fmac_f32_e32 v37, v53, v49
	v_fmac_f32_e32 v37, v54, v50
	v_fmac_f32_e32 v37, v55, v51
	ds_read_b128 v[48:51], v64 offset:33552
	v_pk_mul_f32 v[46:47], v[46:47], s[60:61] op_sel_hi:[1,0]
	s_waitcnt lgkmcnt(0)
	v_fmac_f32_e32 v37, v56, v48
	v_fmac_f32_e32 v37, v57, v49
	v_pk_mul_f32 v[48:49], v[8:9], v[50:51]
	s_nop 0
	v_add_f32_e32 v37, v37, v48
	v_add_f32_e32 v37, v37, v49
	ds_read_b128 v[48:51], v64 offset:33568
	s_waitcnt lgkmcnt(0)
	v_pk_mul_f32 v[48:49], v[10:11], v[48:49]
	s_nop 0
	v_add_f32_e32 v37, v37, v48
	v_add_f32_e32 v37, v37, v49
	v_pk_mul_f32 v[48:49], v[12:13], v[50:51]
	s_nop 0
	v_add_f32_e32 v37, v37, v48
	v_add_f32_e32 v37, v37, v49
	ds_read_b128 v[48:51], v64 offset:33584
	s_waitcnt lgkmcnt(0)
; DI float logsigf_(float x) { return fminf(x, 0.f) - __logf(1.f + __expf(-fabsf(x))); }
; DN void gla_state_item(const Params& p, int l, int item, char* smem) {
;     ...
; #pragma unroll
;       for (int li = 0; li < 8; ++li) {
;         int lt = lgrp * 8 + li;
;         float x = abv;
; #pragma unroll
;         for (int q = 0; q < 16; ++q) x += gg[lt * 16 + q] * a2c[q];
;         lgv[li] = logsigf_(x) * (1.f / 16.f);
;       }
;       if (dir == 0) {
; #pragma unroll
;         for (int li = 1; li < 8; ++li) lgv[li] += lgv[li - 1];
;         segs[lgrp * 32 + dl] = lgv[7];
	v_pk_mul_f32 v[48:49], v[14:15], v[48:49]
	s_nop 0
	v_add_f32_e32 v37, v37, v48
	v_add_f32_e32 v37, v37, v49
	v_pk_mul_f32 v[48:49], v[16:17], v[50:51]
	s_nop 0
	v_add_f32_e32 v37, v37, v48
	v_add_f32_e32 v37, v37, v49
	v_min_f32_e32 v48, 0, v37
	v_mul_f32_e64 v37, |v37|, s57
	v_exp_f32_e32 v37, v37
	s_nop 0
	v_add_f32_e32 v37, 1.0, v37
	v_cmp_gt_f32_e32 vcc, s33, v37
	s_nop 1
	v_cndmask_b32_e64 v39, 0, 32, vcc
	v_ldexp_f32 v37, v37, v39
	v_log_f32_e32 v37, v37
	s_nop 0
	v_mul_f32_e32 v39, 0x3f317217, v37
	v_fma_f32 v39, v37, s59, -v39
	v_fmac_f32_e32 v39, 0x3377d1cf, v37
	v_fmac_f32_e32 v39, 0x3f317217, v37
	v_cmp_lt_f32_e64 s[42:43], |v37|, s58
	s_nop 1
	v_cndmask_b32_e64 v37, v37, v39, s[42:43]
	v_cndmask_b32_e32 v39, 0, v196, vcc
	v_sub_f32_e32 v50, v37, v39
	v_fma_f32 v37, v52, v66, v58
	v_fmac_f32_e32 v37, v53, v67
	v_fmac_f32_e32 v37, v54, v68
	v_fmac_f32_e32 v37, v55, v69
	ds_read_b128 v[66:69], v64 offset:33616
	s_waitcnt lgkmcnt(0)
	v_fmac_f32_e32 v37, v56, v66
	v_fmac_f32_e32 v37, v57, v67
	v_pk_mul_f32 v[66:67], v[8:9], v[68:69]
	s_nop 0
	v_add_f32_e32 v37, v37, v66
	v_add_f32_e32 v37, v37, v67
	ds_read_b128 v[66:69], v64 offset:33632
	s_waitcnt lgkmcnt(0)
	v_pk_mul_f32 v[66:67], v[10:11], v[66:67]
	s_nop 0
	v_add_f32_e32 v37, v37, v66
	v_add_f32_e32 v37, v37, v67
	v_pk_mul_f32 v[66:67], v[12:13], v[68:69]
	s_nop 0
	v_add_f32_e32 v37, v37, v66
	v_add_f32_e32 v37, v37, v67
	ds_read_b128 v[66:69], v64 offset:33648
	s_waitcnt lgkmcnt(0)
	v_pk_mul_f32 v[66:67], v[14:15], v[66:67]
	s_nop 0
	v_add_f32_e32 v37, v37, v66
	v_add_f32_e32 v37, v37, v67
	v_pk_mul_f32 v[66:67], v[16:17], v[68:69]
	s_nop 0
	v_add_f32_e32 v37, v37, v66
	v_add_f32_e32 v37, v37, v67
	v_min_f32_e32 v49, 0, v37
	v_mul_f32_e64 v37, |v37|, s57
	v_exp_f32_e32 v37, v37
	ds_read_b128 v[66:69], v64 offset:33664
	v_add_f32_e32 v37, 1.0, v37
	v_cmp_gt_f32_e32 vcc, s33, v37
	s_nop 1
	v_cndmask_b32_e64 v39, 0, 32, vcc
	v_ldexp_f32 v37, v37, v39
	v_log_f32_e32 v37, v37
	s_nop 0
	v_mul_f32_e32 v39, 0x3f317217, v37
	v_fma_f32 v39, v37, s59, -v39
	v_fmac_f32_e32 v39, 0x3377d1cf, v37
	v_fmac_f32_e32 v39, 0x3f317217, v37
	v_cmp_lt_f32_e64 s[42:43], |v37|, s58
	s_nop 1
	v_cndmask_b32_e64 v37, v37, v39, s[42:43]
	v_cndmask_b32_e32 v39, 0, v196, vcc
	v_sub_f32_e32 v51, v37, v39
	s_waitcnt lgkmcnt(0)
	v_fma_f32 v37, v52, v66, v58
	v_fmac_f32_e32 v37, v53, v67
	v_fmac_f32_e32 v37, v54, v68
	v_fmac_f32_e32 v37, v55, v69
	ds_read_b128 v[66:69], v64 offset:33680
	v_pk_add_f32 v[48:49], v[48:49], v[50:51] neg_lo:[0,1] neg_hi:[0,1]
	s_waitcnt lgkmcnt(0)
	v_fmac_f32_e32 v37, v56, v66
	v_fmac_f32_e32 v37, v57, v67
	v_pk_mul_f32 v[50:51], v[8:9], v[68:69]
	ds_read_b128 v[66:69], v64 offset:33696
	v_add_f32_e32 v37, v37, v50
	v_add_f32_e32 v37, v37, v51
	v_pk_mul_f32 v[48:49], v[48:49], s[60:61] op_sel_hi:[1,0]
	s_waitcnt lgkmcnt(0)
	v_pk_mul_f32 v[50:51], v[10:11], v[66:67]
	s_nop 0
	v_add_f32_e32 v37, v37, v50
	v_add_f32_e32 v37, v37, v51
	v_pk_mul_f32 v[50:51], v[12:13], v[68:69]
	ds_read_b128 v[66:69], v64 offset:33712
	v_add_f32_e32 v37, v37, v50
	v_add_f32_e32 v37, v37, v51
	s_waitcnt lgkmcnt(0)
	v_pk_mul_f32 v[50:51], v[14:15], v[66:67]
	s_nop 0
	v_add_f32_e32 v37, v37, v50
	v_add_f32_e32 v37, v37, v51
	v_pk_mul_f32 v[50:51], v[16:17], v[68:69]
	ds_read_b128 v[66:69], v64 offset:33728
	v_add_f32_e32 v37, v37, v50
	v_add_f32_e32 v37, v37, v51
	v_min_f32_e32 v50, 0, v37
	v_mul_f32_e64 v37, |v37|, s57
	v_exp_f32_e32 v37, v37
	s_nop 0
	v_add_f32_e32 v37, 1.0, v37
	v_cmp_gt_f32_e32 vcc, s33, v37
	s_nop 1
	v_cndmask_b32_e64 v39, 0, 32, vcc
	v_ldexp_f32 v37, v37, v39
	v_log_f32_e32 v37, v37
	s_nop 0
	v_mul_f32_e32 v39, 0x3f317217, v37
	v_fma_f32 v39, v37, s59, -v39
	v_fmac_f32_e32 v39, 0x3377d1cf, v37
	v_fmac_f32_e32 v39, 0x3f317217, v37
	v_cmp_lt_f32_e64 s[42:43], |v37|, s58
	s_nop 1
	v_cndmask_b32_e64 v37, v37, v39, s[42:43]
	v_cndmask_b32_e32 v39, 0, v196, vcc
	v_sub_f32_e32 v70, v37, v39
	s_waitcnt lgkmcnt(0)
	v_fma_f32 v37, v52, v66, v58
	v_fmac_f32_e32 v37, v53, v67
	v_fmac_f32_e32 v37, v54, v68
	v_fmac_f32_e32 v37, v55, v69
	ds_read_b128 v[66:69], v64 offset:33744
	s_waitcnt lgkmcnt(0)
	v_fmac_f32_e32 v37, v56, v66
	v_fmac_f32_e32 v37, v57, v67
	v_pk_mul_f32 v[66:67], v[8:9], v[68:69]
	s_nop 0
	v_add_f32_e32 v37, v37, v66
	v_add_f32_e32 v37, v37, v67
	ds_read_b128 v[66:69], v64 offset:33760
	s_waitcnt lgkmcnt(0)
	v_pk_mul_f32 v[66:67], v[10:11], v[66:67]
	s_nop 0
	v_add_f32_e32 v37, v37, v66
	v_add_f32_e32 v37, v37, v67
	v_pk_mul_f32 v[66:67], v[12:13], v[68:69]
	s_nop 0
	v_add_f32_e32 v37, v37, v66
	v_add_f32_e32 v37, v37, v67
	ds_read_b128 v[66:69], v64 offset:33776
	s_waitcnt lgkmcnt(0)
	v_pk_mul_f32 v[66:67], v[14:15], v[66:67]
	s_nop 0
	v_add_f32_e32 v37, v37, v66
	v_add_f32_e32 v37, v37, v67
	v_pk_mul_f32 v[66:67], v[16:17], v[68:69]
	s_nop 0
	v_add_f32_e32 v37, v37, v66
	v_add_f32_e32 v37, v37, v67
	v_min_f32_e32 v51, 0, v37
	v_mul_f32_e64 v37, |v37|, s57
	v_exp_f32_e32 v37, v37
	s_nop 0
	v_add_f32_e32 v37, 1.0, v37
	v_cmp_gt_f32_e32 vcc, s33, v37
	s_nop 1
	v_cndmask_b32_e64 v39, 0, 32, vcc
	v_ldexp_f32 v37, v37, v39
	v_log_f32_e32 v37, v37
	s_nop 0
	v_mul_f32_e32 v39, 0x3f317217, v37
	v_fma_f32 v39, v37, s59, -v39
	v_fmac_f32_e32 v39, 0x3377d1cf, v37
	v_fmac_f32_e32 v39, 0x3f317217, v37
	v_cmp_lt_f32_e64 s[42:43], |v37|, s58
	s_mov_b64 s[58:59], -1
	s_nop 0
	v_cndmask_b32_e64 v37, v37, v39, s[42:43]
	v_cndmask_b32_e32 v39, 0, v196, vcc
	v_sub_f32_e32 v71, v37, v39
	v_pk_add_f32 v[50:51], v[50:51], v[70:71] neg_lo:[0,1] neg_hi:[0,1]
	v_cndmask_b32_e64 v37, 0, 1, s[54:55]
	v_pk_mul_f32 v[50:51], v[50:51], s[60:61] op_sel_hi:[1,0]
	v_cmp_ne_u32_e64 s[42:43], 1, v37
	s_andn2_b64 vcc, exec, s[54:55]
	s_cbranch_vccnz .LBB0_438
	v_add_f32_e32 v37, v50, v51
	v_add_f32_e32 v39, v49, v37
	v_add_f32_e32 v41, v48, v39
	v_add_f32_e32 v43, v47, v41
	v_add_f32_e32 v66, v46, v43
	v_add_f32_e32 v67, v45, v66
	v_add_f32_e32 v68, v44, v67
	s_mov_b64 s[58:59], 0
	v_mov_b32_e32 v69, v68

; DN void gla_state_item(const Params& p, int l, int item, char* smem) {
;     ...
;         segs[lgrp * 32 + dl] = lgv[7];
;       } else {
; #pragma unroll
;     ...
;         segs[lgrp * 32 + dl] = lgv[0];
;       }
;       vsync_l();
;       float off = 0.f, tot = 0.f;
; #pragma unroll
;       for (int sg = 0; sg < 8; ++sg) {
;         const float sv = segs[sg * 32 + dl];
;         tot += sv;
;         if ((dir == 0) ? (sg < lgrp) : (sg > lgrp)) off += sv;
.LBB0_440:
	ds_write_b32 v60, v69 offset:37504
	s_waitcnt lgkmcnt(0)
	s_waitcnt lgkmcnt(0)
	s_barrier
	ds_read_b32 v44, v26 offset:37504
	s_and_b64 vcc, exec, s[54:55]
	s_cbranch_vccz .LBB0_446
	s_and_b64 s[58:59], s[8:9], exec
	s_cbranch_execz .LBB0_447
	s_branch .LBB0_448

; DN void gla_state_item(const Params& p, int l, int item, char* smem) {
;     ...
;       for (int li = 0; li < 8; ++li) bb[(lgrp * 8 + li) * 33 + dl] = lgv[li] + off;
;       if (lgrp == 0) sbend[dl] = tot;
;     }
;     vsync_l();
;     for (int i = tid; i < 2048; i += 256) { int li = i >> 5, dd = i & 31; kk_[li * 33 + dd] *= __expf(sbend[dd] - bb[li * 33 + dd]); }
.LBB0_480:
	s_or_b64 exec, exec, s[42:43]
	s_waitcnt lgkmcnt(0)
	s_waitcnt lgkmcnt(0)
	s_barrier
	s_and_saveexec_b64 s[42:43], s[6:7]
	s_cbranch_execz .LBB0_487
	s_mov_b64 s[58:59], 0
	v_mov_b32_e32 v37, v27

; DN void gla_state_item(const Params& p, int l, int item, char* smem) {
;     ...
;     {
;       float* dst = GS + ((((size_t)b * 36 + cs) * 4 + hh) * 2 + dir) * 2048 + d * 64 + e0;
;       *(float4*)dst = make_float4(S[0], S[1], S[2], S[3]);
;       *(float4*)(dst + 4) = make_float4(S[4], S[5], S[6], S[7]);
;     }
;     vsync();
;     float dec = __expf(sbend[d]);
; #pragma unroll
;     for (int e = 0; e < 8; ++e) S[e] *= dec;
.LBB0_487:
	s_or_b64 exec, exec, s[42:43]
	s_ashr_i32 s57, s56, 31
	v_lshl_add_u64 v[44:45], v[28:29], 0, s[56:57]
	v_lshlrev_b64 v[44:45], 16, v[44:45]
	v_lshl_add_u64 v[44:45], v[34:35], 0, v[44:45]
	global_store_dwordx4 v[44:45], v[0:3], off
	global_store_dwordx4 v[44:45], v[4:7], off offset:16
	s_waitcnt lgkmcnt(0)
	s_waitcnt lgkmcnt(0)
	s_barrier
	ds_read_b32 v37, v61 offset:37376
	s_mov_b32 s42, 0
	s_waitcnt lgkmcnt(0)
	v_mul_f32_e32 v37, 0x3fb8aa3b, v37
	v_exp_f32_e32 v44, v37
	v_mov_b32_e32 v37, v33
	v_pk_mul_f32 v[6:7], v[6:7], v[44:45] op_sel_hi:[1,0]
	v_pk_mul_f32 v[4:5], v[4:5], v[44:45] op_sel_hi:[1,0]
	v_pk_mul_f32 v[2:3], v[2:3], v[44:45] op_sel_hi:[1,0]
	v_pk_mul_f32 v[0:1], v[0:1], v[44:45] op_sel_hi:[1,0]
